# GEMM K loop: per-cluster s_setprio flips removed, one static priority raise for waves 4-7 per tile
# speedup vs baseline: 1.0120x; 1.0059x over previous
; DEVI int ltid() { int t = __builtin_amdgcn_workitem_id_x(); asm volatile("" : "+v"(t)); return t; }
; #define STAGE(bufoff,gbase,voff) do{ _Pragma("unroll") for(int _i=0;_i<2;++_i) \
;     __builtin_amdgcn_global_load_lds((const unsigned*)((const char*)(gbase)+(voff)[_i]),(LAS unsigned*)(lds+(bufoff)+ldsw+_i*8192),16,0,0);}while(0)
; #define BAR __builtin_amdgcn_s_barrier()
; DEVI void gemm_tile(const GJob& jb, int brow, int bcol, unsigned char* shm_) {
;     ...
;   const int tid = ltid(), wid = __builtin_amdgcn_readfirstlane(tid >> 6), lane = tid & 63, wr = wid >> 2, wc = wid & 3, fr = lane & 15, fq = lane >> 4;
;   unsigned voffA[2], voffB[2];
; #pragma unroll
;   for (int i = 0; i < 2; ++i) { int R, C; stage_rc(tid * 16 + i * 8192, R, C); const int Rb = (R & ~31) + perm32(R & 31); voffA[i] = (unsigned)(R * lda + C) * 2u; voffB[i] = (unsigned)(Rb * ldb + C) * 2u; }
;   const size_t hA = (size_t)HALF * lda * 2, hB = (size_t)HALF * ldb * 2;
;   const unsigned ldsw = (unsigned)wid * 1024u;
;   const int aoff = lds_byte(wr * 64 + fr, fq * 8), boff = lds_byte(wc * 32 + fr, fq * 8);
;   constexpr int HTB = HT * 2;
;     ...
;   f32x4 acc[2][2][4][2];
; #pragma unroll
;   for (int a = 0; a < 2; ++a)
; #pragma unroll
;     for (int b = 0; b < 2; ++b)
; #pragma unroll
;       for (int m = 0; m < 4; ++m)
; #pragma unroll
;         for (int n = 0; n < 2; ++n) acc[a][b][m][n] = (f32x4){0.f, 0.f, 0.f, 0.f};
;   bf16x8 At[4][2], B0[2][2], B1[2][2];
;   const int nt = K / BK;
;   const char* cA = (const char*)jb.A + (size_t)brow * lda * 2; const char* cB = (const char*)jb.Bt + (size_t)bcol * ldb * 2;
;   STAGE(SB(0,0),cB,voffB); STAGE(SA(0,0),cA,voffA);
;   STAGE(SB(0,1),cB+hB,voffB); STAGE(SA(0,1),cA+hA,voffA);
;   if (wr == 1) BAR;
; DEVI void gemm_job(const GJob& jb, int& cursor, int c, int G, unsigned char* lds) {
;     ...
;       const int nig = WGM * nN, gid = i / nig, fm = gid * WGM, gsz = (nM - fm) < WGM ? (nM - fm) : WGM;
;       const int pm = fm + ((i % nig) % gsz), pn = (i % nig) / gsz;
;       gemm_tile(jb, pm * BM, pn * BM, lds);
.LBB0_410:
	s_abs_i32 s1, s20
	s_mul_hi_u32 s4, s1, s48
	s_mul_i32 s5, s4, s14
	s_ashr_i32 s0, s20, 31
	s_sub_i32 s1, s1, s5
	s_xor_b32 s0, s0, s15
	s_add_i32 s5, s4, 1
	s_sub_i32 s8, s1, s14
	s_cmp_ge_u32 s1, s14
	s_cselect_b32 s4, s5, s4
	s_cselect_b32 s1, s8, s1
	s_add_i32 s5, s4, 1
	s_cmp_ge_u32 s1, s14
	s_cselect_b32 s1, s5, s4
	s_xor_b32 s1, s1, s0
	s_sub_i32 s5, s1, s0
	s_lshl_b32 s4, s5, 3
	s_sub_i32 s8, 32, s4
	s_min_i32 s8, s8, 8
	s_abs_i32 s9, s8
	v_cvt_f32_u32_e32 v0, s9
	s_sub_i32 s13, 0, s9
	s_mul_i32 s5, s5, s21
	s_sub_i32 s10, s20, s5
	v_rcp_iflag_f32_e32 v0, v0
	s_abs_i32 s12, s10
	s_xor_b32 s11, s10, s8
	s_ashr_i32 s11, s11, 31
	v_mul_f32_e32 v0, 0x4f7ffffe, v0
	v_cvt_u32_f32_e32 v0, v0
	s_nop 0
	v_mov_b32_e32 v137, v169
	v_readfirstlane_b32 s16, v0
	s_mul_i32 s13, s13, s16
	s_mul_hi_u32 s13, s16, s13
	s_add_i32 s16, s16, s13
	s_mul_hi_u32 s13, s12, s16
	s_mul_i32 s16, s13, s9
	s_sub_i32 s12, s12, s16
	s_add_i32 s16, s13, 1
	s_sub_i32 s17, s12, s9
	s_cmp_ge_u32 s12, s9
	s_cselect_b32 s13, s16, s13
	s_cselect_b32 s12, s17, s12
	s_add_i32 s16, s13, 1
	s_cmp_ge_u32 s12, s9
	s_cselect_b32 s9, s16, s13
	s_xor_b32 s9, s9, s11
	s_sub_i32 s9, s9, s11
	s_mul_i32 s58, s9, s8
	s_sub_i32 s8, s10, s58
	s_add_i32 s8, s8, s4
	s_lshl_b32 s43, s8, 8
	s_nop 0
	v_ashrrev_i32_e32 v141, 3, v137
	s_nop 0
	v_lshrrev_b32_e32 v5, 2, v141
	s_ashr_i32 s4, s43, 31
	s_lshl_b32 s12, s9, 8
	v_lshlrev_b32_e32 v140, 4, v137
	v_lshrrev_b32_e32 v2, 1, v137
	v_and_b32_e32 v133, 0x7fffffe0, v141
	v_and_b32_e32 v134, 4, v5
	s_mul_i32 s4, s66, s4
	s_mul_hi_u32 s8, s66, s43
	v_bfe_u32 v132, v140, 6, 2
	v_or_b32_e32 v5, v134, v133
	v_and_b32_e32 v158, 24, v2
	s_add_i32 s4, s8, s4
	s_mul_i32 s8, s67, s43
	s_ashr_i32 s13, s12, 31
	v_readfirstlane_b32 s46, v137
	v_and_b32_e32 v131, 32, v2
	v_or3_b32 v2, v5, v158, v132
	v_add_u32_e32 v5, 0x2000, v140
	s_add_i32 s11, s4, s8
	s_mul_i32 s4, s30, s13
	s_mul_hi_u32 s8, s30, s12
	v_and_b32_e32 v0, 32, v137
	v_ashrrev_i32_e32 v142, 7, v5
	s_ashr_i32 s57, s46, 6
	s_add_i32 s4, s8, s4
	s_mul_i32 s8, s31, s12
	s_ashr_i32 s52, s46, 8
	v_bitop3_b32 v0, v140, v0, 48 bitop3:0x6c
	v_lshrrev_b32_e32 v5, 2, v142
	s_lshl_b32 s16, s57, 10
	s_add_i32 s4, s4, s8
	s_mul_i32 s53, s30, s12
	v_bfe_u32 v3, v137, 2, 26
	v_lshrrev_b32_e32 v130, 1, v0
	v_and_b32_e32 v135, 0x7fffffe0, v142
	v_and_b32_e32 v136, 4, v5
	s_add_u32 s8, s60, s53
	v_or_b32_e32 v4, v130, v131
	v_bfi_b32 v0, 15, v3, v141
	v_mul_lo_u32 v2, v2, s18
	v_bfi_b32 v3, -16, v142, v3
	v_or_b32_e32 v5, v135, v136
	s_addc_u32 s9, s61, s4
	s_add_i32 s69, s16, 16
	v_add_lshl_u32 v2, v2, v4, 1
	v_or3_b32 v5, v5, v158, v132
	v_mul_lo_u32 v3, v3, s96
	s_add_i32 m0, s69, 0x10000
	v_mul_lo_u32 v0, v0, s96
	v_add_lshl_u32 v138, v3, v4, 1
	v_mul_lo_u32 v3, v5, s18
	s_mul_i32 s10, s66, s43
	global_load_lds_dwordx4 v2, s[8:9]
	s_add_i32 m0, s69, 0x12000
	v_add_lshl_u32 v0, v0, v4, 1
	v_add_lshl_u32 v4, v3, v4, 1
	s_add_u32 s10, s40, s10
	global_load_lds_dwordx4 v4, s[8:9]
	s_addc_u32 s11, s41, s11
	s_mov_b32 m0, s69
	s_add_i32 s17, s69, 0x2000
	global_load_lds_dwordx4 v0, s[10:11]
	s_mov_b32 m0, s17
	s_add_u32 s82, s8, s64
	global_load_lds_dwordx4 v138, s[10:11]
	s_addc_u32 s83, s9, s65
	s_add_i32 m0, s69, 0x14000
	s_nop 0
	global_load_lds_dwordx4 v2, s[82:83]
	s_add_i32 m0, s69, 0x16000
	s_add_u32 s44, s10, s26
	s_addc_u32 s45, s11, s27
	s_add_i32 s34, s69, 0x4000
	global_load_lds_dwordx4 v4, s[82:83]
	s_mov_b32 m0, s34
	s_add_i32 s81, s69, 0x6000
	global_load_lds_dwordx4 v0, s[44:45]
	s_mov_b32 m0, s81
	s_cmp_lg_u32 s52, 1
	global_load_lds_dwordx4 v138, s[44:45]
	s_cbranch_scc1 .LBB0_412
	s_setprio 1
	s_barrier

; #define STAGE(bufoff,gbase,voff) do{ _Pragma("unroll") for(int _i=0;_i<2;++_i) \
;     __builtin_amdgcn_global_load_lds((const unsigned*)((const char*)(gbase)+(voff)[_i]),(LAS unsigned*)(lds+(bufoff)+ldsw+_i*8192),16,0,0);}while(0)
; #define LDA(dst,b,h) do{ _Pragma("unroll") for(int m=0;m<4;++m) _Pragma("unroll") for(int k=0;k<2;++k) dst[m][k]=*(const LAS bf16x8*)(lds+SA(b,h)+aoff+m*2048+k*1024);}while(0)
; #define LDB(dst,b,h) do{ _Pragma("unroll") for(int n=0;n<2;++n) _Pragma("unroll") for(int k=0;k<2;++k) dst[n][k]=*(const LAS bf16x8*)(lds+SB(b,h)+boff+n*2048+k*1024);}while(0)
; #define MMA(ai,bj,At_,Bt_) do{__builtin_amdgcn_s_setprio(1); \
;     _Pragma("unroll") for(int m=0;m<4;++m) _Pragma("unroll") for(int n=0;n<2;++n) _Pragma("unroll") for(int k=0;k<2;++k) \
;       acc[ai][bj][m][n]=__builtin_amdgcn_mfma_f32_16x16x32_bf16(Bt_[n][k],At_[m][k],acc[ai][bj][m][n],0,0,0); \
;     __builtin_amdgcn_s_setprio(0);}while(0)
; #define WAIT_V(n) asm volatile("s_waitcnt vmcnt(" #n ")":::"memory")
; #define WAIT_L(n) asm volatile("s_waitcnt lgkmcnt(" #n ")":::"memory")
; #define BAR __builtin_amdgcn_s_barrier()
; #define SCHED __builtin_amdgcn_sched_barrier(0)
; DEVI void gemm_tile(const GJob& jb, int brow, int bcol, unsigned char* shm_) {
;     ...
;     LDB(B0,0,0); SCHED; LDA(At,0,0); STAGE(SA(1,1),a1+hA,voffA);
;     WAIT_L(8); BAR; WAIT_L(0); MMA(0,0,At,B0); BAR; SCHED;
;     LDB(B1,0,1); STAGE(SB(0,0),b2,voffB);
;     BAR; WAIT_L(0); MMA(0,1,At,B1); BAR;
;     LDA(At,0,1); STAGE(SA(0,0),a2,voffA);
;     BAR; WAIT_L(0); MMA(1,0,At,B0); BAR; SCHED;
;     STAGE(SB(0,1),b2+hB,voffB);
;     WAIT_V(6); BAR; MMA(1,1,At,B1); BAR;
;     LDB(B0,1,0); SCHED; LDA(At,1,0); STAGE(SA(0,1),a2+hA,voffA);
;     WAIT_L(8); BAR; WAIT_L(0); MMA(0,0,At,B0); BAR; SCHED;
.LBB0_414:
	s_add_i32 s0, 16, 0x10000
	v_add_u32_e32 v166, s0, v161
	ds_read_b128 v[130:133], v166
	ds_read_b128 v[134:137], v166 offset:1024
	ds_read_b128 v[162:165], v166 offset:2048
	ds_read_b128 v[170:173], v166 offset:3072
	s_add_i32 s13, s13, 2
	v_lshl_add_u64 v[166:167], v[142:143], 0, s[82:83]
	v_add_u32_e32 v168, 16, v160
	v_lshl_add_u64 v[178:179], v[166:167], 0, s[72:73]
	s_add_i32 m0, s69, 0xc000
	ds_read_b128 v[174:177], v168
	ds_read_b128 v[194:197], v168 offset:1024
	ds_read_b128 v[198:201], v168 offset:2048
	ds_read_b128 v[202:205], v168 offset:3072
	ds_read_b128 v[206:209], v168 offset:4096
	ds_read_b128 v[210:213], v168 offset:5120
	ds_read_b128 v[214:217], v168 offset:6144
	ds_read_b128 v[218:221], v168 offset:7168
	global_load_lds_dwordx4 v[178:179], off
	v_lshl_add_u64 v[178:179], v[144:145], 0, s[82:83]
	v_lshl_add_u64 v[222:223], v[178:179], 0, s[72:73]
	s_add_i32 m0, s69, 0xe000
	s_nop 0
	global_load_lds_dwordx4 v[222:223], off
	s_waitcnt lgkmcnt(8)
	s_barrier
	s_waitcnt lgkmcnt(0)
	s_waitcnt lgkmcnt(0)
	v_mfma_f32_16x16x32_bf16 v[122:125], v[130:133], v[174:177], v[122:125]
	v_mfma_f32_16x16x32_bf16 v[126:129], v[162:165], v[174:177], v[126:129]
	v_mfma_f32_16x16x32_bf16 v[118:121], v[130:133], v[198:201], v[118:121]
	v_mfma_f32_16x16x32_bf16 v[114:117], v[162:165], v[198:201], v[114:117]
	v_mfma_f32_16x16x32_bf16 v[110:113], v[130:133], v[206:209], v[110:113]
	v_mfma_f32_16x16x32_bf16 v[106:109], v[162:165], v[206:209], v[106:109]
	v_mfma_f32_16x16x32_bf16 v[102:105], v[130:133], v[214:217], v[102:105]
	v_mfma_f32_16x16x32_bf16 v[98:101], v[162:165], v[214:217], v[98:101]
	v_mfma_f32_16x16x32_bf16 v[122:125], v[134:137], v[194:197], v[122:125]
	v_mfma_f32_16x16x32_bf16 v[126:129], v[170:173], v[194:197], v[126:129]
	v_mfma_f32_16x16x32_bf16 v[118:121], v[134:137], v[202:205], v[118:121]
	v_mfma_f32_16x16x32_bf16 v[114:117], v[170:173], v[202:205], v[114:117]
	v_mfma_f32_16x16x32_bf16 v[110:113], v[134:137], v[210:213], v[110:113]
	v_mfma_f32_16x16x32_bf16 v[106:109], v[170:173], v[210:213], v[106:109]
	v_mfma_f32_16x16x32_bf16 v[102:105], v[134:137], v[218:221], v[102:105]
	v_mfma_f32_16x16x32_bf16 v[98:101], v[170:173], v[218:221], v[98:101]
	s_barrier
	s_add_i32 s1, 16, 0x14000
	v_lshl_add_u64 v[238:239], v[154:155], 0, s[82:83]
	s_add_i32 s0, s0, s16
	v_add_u32_e32 v193, s1, v161
	v_lshl_add_u64 v[240:241], v[238:239], 0, s[76:77]
	s_mov_b32 m0, s0
	ds_read_b128 v[222:225], v193
	ds_read_b128 v[226:229], v193 offset:1024
	ds_read_b128 v[230:233], v193 offset:2048
	ds_read_b128 v[234:237], v193 offset:3072
	global_load_lds_dwordx4 v[240:241], off
	v_lshl_add_u64 v[240:241], v[152:153], 0, s[82:83]
	v_lshl_add_u64 v[242:243], v[240:241], 0, s[76:77]
	s_add_i32 m0, s0, 0x2000
	s_nop 0
	global_load_lds_dwordx4 v[242:243], off
	s_barrier
	s_waitcnt lgkmcnt(0)
	s_waitcnt lgkmcnt(0)
	v_mfma_f32_16x16x32_bf16 v[94:97], v[222:225], v[174:177], v[94:97]
	v_mfma_f32_16x16x32_bf16 v[90:93], v[230:233], v[174:177], v[90:93]
	v_mfma_f32_16x16x32_bf16 v[86:89], v[222:225], v[198:201], v[86:89]
	v_mfma_f32_16x16x32_bf16 v[82:85], v[230:233], v[198:201], v[82:85]
	v_mfma_f32_16x16x32_bf16 v[78:81], v[222:225], v[206:209], v[78:81]
	v_mfma_f32_16x16x32_bf16 v[74:77], v[230:233], v[206:209], v[74:77]
	v_mfma_f32_16x16x32_bf16 v[70:73], v[222:225], v[214:217], v[70:73]
	v_mfma_f32_16x16x32_bf16 v[66:69], v[230:233], v[214:217], v[66:69]
	v_mfma_f32_16x16x32_bf16 v[94:97], v[226:229], v[194:197], v[94:97]
	v_mfma_f32_16x16x32_bf16 v[90:93], v[234:237], v[194:197], v[90:93]
	v_mfma_f32_16x16x32_bf16 v[86:89], v[226:229], v[202:205], v[86:89]
	v_mfma_f32_16x16x32_bf16 v[82:85], v[234:237], v[202:205], v[82:85]
	v_mfma_f32_16x16x32_bf16 v[78:81], v[226:229], v[210:213], v[78:81]
	v_mfma_f32_16x16x32_bf16 v[74:77], v[234:237], v[210:213], v[74:77]
	v_mfma_f32_16x16x32_bf16 v[70:73], v[226:229], v[218:221], v[70:73]
	v_mfma_f32_16x16x32_bf16 v[66:69], v[234:237], v[218:221], v[66:69]
	v_lshl_add_u64 v[242:243], v[146:147], 0, s[82:83]
	s_mov_b32 m0, s69
	v_lshl_add_u64 v[244:245], v[242:243], 0, s[76:77]
	s_barrier
	ds_read_b128 v[174:177], v168 offset:16384
	ds_read_b128 v[194:197], v168 offset:17408
	ds_read_b128 v[198:201], v168 offset:18432
	ds_read_b128 v[202:205], v168 offset:19456
	ds_read_b128 v[206:209], v168 offset:20480
	ds_read_b128 v[210:213], v168 offset:21504
	ds_read_b128 v[214:217], v168 offset:22528
	ds_read_b128 v[218:221], v168 offset:23552
	global_load_lds_dwordx4 v[244:245], off
	v_lshl_add_u64 v[244:245], v[156:157], 0, s[82:83]
	v_lshl_add_u64 v[246:247], v[244:245], 0, s[76:77]
	s_mov_b32 m0, s17
	s_nop 0
	global_load_lds_dwordx4 v[246:247], off
	s_barrier
	s_waitcnt lgkmcnt(0)
	s_waitcnt lgkmcnt(0)
	v_mfma_f32_16x16x32_bf16 v[62:65], v[130:133], v[174:177], v[62:65]
	v_mfma_f32_16x16x32_bf16 v[58:61], v[162:165], v[174:177], v[58:61]
	v_mfma_f32_16x16x32_bf16 v[54:57], v[130:133], v[198:201], v[54:57]
	v_mfma_f32_16x16x32_bf16 v[50:53], v[162:165], v[198:201], v[50:53]
	v_mfma_f32_16x16x32_bf16 v[46:49], v[130:133], v[206:209], v[46:49]
	v_mfma_f32_16x16x32_bf16 v[42:45], v[162:165], v[206:209], v[42:45]
	v_mfma_f32_16x16x32_bf16 v[38:41], v[130:133], v[214:217], v[38:41]
	v_mfma_f32_16x16x32_bf16 v[34:37], v[162:165], v[214:217], v[34:37]
	v_mfma_f32_16x16x32_bf16 v[62:65], v[134:137], v[194:197], v[62:65]
	v_mfma_f32_16x16x32_bf16 v[58:61], v[170:173], v[194:197], v[58:61]
	v_mfma_f32_16x16x32_bf16 v[54:57], v[134:137], v[202:205], v[54:57]
	v_mfma_f32_16x16x32_bf16 v[50:53], v[170:173], v[202:205], v[50:53]
	v_mfma_f32_16x16x32_bf16 v[46:49], v[134:137], v[210:213], v[46:49]
	v_mfma_f32_16x16x32_bf16 v[42:45], v[170:173], v[210:213], v[42:45]
	v_mfma_f32_16x16x32_bf16 v[38:41], v[134:137], v[218:221], v[38:41]
	v_mfma_f32_16x16x32_bf16 v[34:37], v[170:173], v[218:221], v[34:37]
	s_barrier
; #define STAGE(bufoff,gbase,voff) do{ _Pragma("unroll") for(int _i=0;_i<2;++_i) \
;     __builtin_amdgcn_global_load_lds((const unsigned*)((const char*)(gbase)+(voff)[_i]),(LAS unsigned*)(lds+(bufoff)+ldsw+_i*8192),16,0,0);}while(0)
; #define LDA(dst,b,h) do{ _Pragma("unroll") for(int m=0;m<4;++m) _Pragma("unroll") for(int k=0;k<2;++k) dst[m][k]=*(const LAS bf16x8*)(lds+SA(b,h)+aoff+m*2048+k*1024);}while(0)
; #define LDB(dst,b,h) do{ _Pragma("unroll") for(int n=0;n<2;++n) _Pragma("unroll") for(int k=0;k<2;++k) dst[n][k]=*(const LAS bf16x8*)(lds+SB(b,h)+boff+n*2048+k*1024);}while(0)
; #define MMA(ai,bj,At_,Bt_) do{__builtin_amdgcn_s_setprio(1); \
;     _Pragma("unroll") for(int m=0;m<4;++m) _Pragma("unroll") for(int n=0;n<2;++n) _Pragma("unroll") for(int k=0;k<2;++k) \
;       acc[ai][bj][m][n]=__builtin_amdgcn_mfma_f32_16x16x32_bf16(Bt_[n][k],At_[m][k],acc[ai][bj][m][n],0,0,0); \
;     __builtin_amdgcn_s_setprio(0);}while(0)
; #define WAIT_V(n) asm volatile("s_waitcnt vmcnt(" #n ")":::"memory")
; #define WAIT_L(n) asm volatile("s_waitcnt lgkmcnt(" #n ")":::"memory")
; #define BAR __builtin_amdgcn_s_barrier()
; #define SCHED __builtin_amdgcn_sched_barrier(0)
; DEVI void gemm_tile(const GJob& jb, int brow, int bcol, unsigned char* shm_) {
;     ...
;     WAIT_V(6); BAR; MMA(1,1,At,B1); BAR;
;     LDB(B0,1,0); SCHED; LDA(At,1,0); STAGE(SA(0,1),a2+hA,voffA);
;     WAIT_L(8); BAR; WAIT_L(0); MMA(0,0,At,B0); BAR; SCHED;
;     LDB(B1,1,1); STAGE(SB(1,0),b3,voffB);
;     BAR; WAIT_L(0); MMA(0,1,At,B1); BAR;
;     LDA(At,1,1); STAGE(SA(1,0),a3,voffA);
;     BAR; WAIT_L(0); MMA(1,0,At,B0); BAR; SCHED;
	v_lshl_add_u64 v[246:247], v[150:151], 0, s[82:83]
	s_add_i32 s0, s1, s16
	v_lshl_add_u64 v[130:131], v[246:247], 0, s[76:77]
	s_mov_b32 m0, s0
	v_lshl_add_u64 v[248:249], v[148:149], 0, s[82:83]
	global_load_lds_dwordx4 v[130:131], off
	v_lshl_add_u64 v[130:131], v[248:249], 0, s[76:77]
	s_add_i32 m0, s0, 0x2000
	s_nop 0
	global_load_lds_dwordx4 v[130:131], off
	s_waitcnt vmcnt(6)
	s_barrier
	v_mfma_f32_16x16x32_bf16 v[30:33], v[222:225], v[174:177], v[30:33]
	v_mfma_f32_16x16x32_bf16 v[26:29], v[230:233], v[174:177], v[26:29]
	v_mfma_f32_16x16x32_bf16 v[22:25], v[222:225], v[198:201], v[22:25]
	v_mfma_f32_16x16x32_bf16 v[18:21], v[230:233], v[198:201], v[18:21]
	v_mfma_f32_16x16x32_bf16 v[14:17], v[222:225], v[206:209], v[14:17]
	v_mfma_f32_16x16x32_bf16 v[10:13], v[230:233], v[206:209], v[10:13]
	v_mfma_f32_16x16x32_bf16 v[6:9], v[222:225], v[214:217], v[6:9]
	v_mfma_f32_16x16x32_bf16 v[2:5], v[230:233], v[214:217], v[2:5]
	v_mfma_f32_16x16x32_bf16 v[30:33], v[226:229], v[194:197], v[30:33]
	v_mfma_f32_16x16x32_bf16 v[26:29], v[234:237], v[194:197], v[26:29]
	v_mfma_f32_16x16x32_bf16 v[22:25], v[226:229], v[202:205], v[22:25]
	v_mfma_f32_16x16x32_bf16 v[18:21], v[234:237], v[202:205], v[18:21]
	v_mfma_f32_16x16x32_bf16 v[14:17], v[226:229], v[210:213], v[14:17]
	v_mfma_f32_16x16x32_bf16 v[10:13], v[234:237], v[210:213], v[10:13]
	v_mfma_f32_16x16x32_bf16 v[6:9], v[226:229], v[218:221], v[6:9]
	v_mfma_f32_16x16x32_bf16 v[2:5], v[234:237], v[218:221], v[2:5]
	s_add_i32 s0, 16, 0x18000
	v_add_u32_e32 v170, s0, v161
	s_barrier
	ds_read_b128 v[130:133], v170
	ds_read_b128 v[134:137], v170 offset:1024
	ds_read_b128 v[162:165], v170 offset:2048
	ds_read_b128 v[170:173], v170 offset:3072
	s_mov_b32 m0, s34
	v_lshl_add_u64 v[166:167], v[166:167], 0, s[76:77]
	ds_read_b128 v[174:177], v168 offset:32768
	ds_read_b128 v[194:197], v168 offset:33792
	ds_read_b128 v[198:201], v168 offset:34816
	ds_read_b128 v[202:205], v168 offset:35840
	ds_read_b128 v[206:209], v168 offset:36864
	ds_read_b128 v[210:213], v168 offset:37888
	ds_read_b128 v[214:217], v168 offset:38912
	ds_read_b128 v[218:221], v168 offset:39936
	global_load_lds_dwordx4 v[166:167], off
	v_lshl_add_u64 v[166:167], v[178:179], 0, s[76:77]
	s_mov_b32 m0, s81
	s_nop 0
	global_load_lds_dwordx4 v[166:167], off
	s_waitcnt lgkmcnt(8)
	s_barrier
	s_waitcnt lgkmcnt(0)
	s_waitcnt lgkmcnt(0)
	v_mfma_f32_16x16x32_bf16 v[122:125], v[130:133], v[174:177], v[122:125]
	v_mfma_f32_16x16x32_bf16 v[126:129], v[162:165], v[174:177], v[126:129]
	v_mfma_f32_16x16x32_bf16 v[118:121], v[130:133], v[198:201], v[118:121]
	v_mfma_f32_16x16x32_bf16 v[114:117], v[162:165], v[198:201], v[114:117]
	v_mfma_f32_16x16x32_bf16 v[110:113], v[130:133], v[206:209], v[110:113]
	v_mfma_f32_16x16x32_bf16 v[106:109], v[162:165], v[206:209], v[106:109]
	v_mfma_f32_16x16x32_bf16 v[102:105], v[130:133], v[214:217], v[102:105]
	v_mfma_f32_16x16x32_bf16 v[98:101], v[162:165], v[214:217], v[98:101]
	v_mfma_f32_16x16x32_bf16 v[122:125], v[134:137], v[194:197], v[122:125]
	v_mfma_f32_16x16x32_bf16 v[126:129], v[170:173], v[194:197], v[126:129]
	v_mfma_f32_16x16x32_bf16 v[118:121], v[134:137], v[202:205], v[118:121]
	v_mfma_f32_16x16x32_bf16 v[114:117], v[170:173], v[202:205], v[114:117]
	v_mfma_f32_16x16x32_bf16 v[110:113], v[134:137], v[210:213], v[110:113]
	v_mfma_f32_16x16x32_bf16 v[106:109], v[170:173], v[210:213], v[106:109]
	v_mfma_f32_16x16x32_bf16 v[102:105], v[134:137], v[218:221], v[102:105]
	v_mfma_f32_16x16x32_bf16 v[98:101], v[170:173], v[218:221], v[98:101]
	s_barrier
	s_add_i32 s1, 16, 0x1c000
	v_add_u32_e32 v166, s1, v161
	s_add_i32 s0, s0, s16
	ds_read_b128 v[222:225], v166
	ds_read_b128 v[226:229], v166 offset:1024
	ds_read_b128 v[230:233], v166 offset:2048
	ds_read_b128 v[234:237], v166 offset:3072
	v_lshl_add_u64 v[166:167], v[238:239], 0, s[38:39]
	s_mov_b32 m0, s0
	s_nop 0
	global_load_lds_dwordx4 v[166:167], off
	v_lshl_add_u64 v[166:167], v[240:241], 0, s[38:39]
	s_add_i32 m0, s0, 0x2000
	s_nop 0
	global_load_lds_dwordx4 v[166:167], off
	s_barrier
; #define STAGE(bufoff,gbase,voff) do{ _Pragma("unroll") for(int _i=0;_i<2;++_i) \
;     __builtin_amdgcn_global_load_lds((const unsigned*)((const char*)(gbase)+(voff)[_i]),(LAS unsigned*)(lds+(bufoff)+ldsw+_i*8192),16,0,0);}while(0)
; #define MMA(ai,bj,At_,Bt_) do{__builtin_amdgcn_s_setprio(1); \
;     _Pragma("unroll") for(int m=0;m<4;++m) _Pragma("unroll") for(int n=0;n<2;++n) _Pragma("unroll") for(int k=0;k<2;++k) \
;       acc[ai][bj][m][n]=__builtin_amdgcn_mfma_f32_16x16x32_bf16(Bt_[n][k],At_[m][k],acc[ai][bj][m][n],0,0,0); \
;     __builtin_amdgcn_s_setprio(0);}while(0)
; #define WAIT_V(n) asm volatile("s_waitcnt vmcnt(" #n ")":::"memory")
; #define WAIT_L(n) asm volatile("s_waitcnt lgkmcnt(" #n ")":::"memory")
; #define BAR __builtin_amdgcn_s_barrier()
; #define SCHED __builtin_amdgcn_sched_barrier(0)
; DEVI void gemm_tile(const GJob& jb, int brow, int bcol, unsigned char* shm_) {
;     ...
;     BAR; WAIT_L(0); MMA(1,0,At,B0); BAR; SCHED;
;     STAGE(SB(1,1),b3+hB,voffB);
;     WAIT_V(6); BAR; MMA(1,1,At,B1); BAR;
	s_waitcnt lgkmcnt(0)
	s_waitcnt lgkmcnt(0)
	v_mfma_f32_16x16x32_bf16 v[94:97], v[222:225], v[174:177], v[94:97]
	v_mfma_f32_16x16x32_bf16 v[90:93], v[230:233], v[174:177], v[90:93]
	v_mfma_f32_16x16x32_bf16 v[86:89], v[222:225], v[198:201], v[86:89]
	v_mfma_f32_16x16x32_bf16 v[82:85], v[230:233], v[198:201], v[82:85]
	v_mfma_f32_16x16x32_bf16 v[78:81], v[222:225], v[206:209], v[78:81]
	v_mfma_f32_16x16x32_bf16 v[74:77], v[230:233], v[206:209], v[74:77]
	v_mfma_f32_16x16x32_bf16 v[70:73], v[222:225], v[214:217], v[70:73]
	v_mfma_f32_16x16x32_bf16 v[66:69], v[230:233], v[214:217], v[66:69]
	v_mfma_f32_16x16x32_bf16 v[94:97], v[226:229], v[194:197], v[94:97]
	v_mfma_f32_16x16x32_bf16 v[90:93], v[234:237], v[194:197], v[90:93]
	v_mfma_f32_16x16x32_bf16 v[86:89], v[226:229], v[202:205], v[86:89]
	v_mfma_f32_16x16x32_bf16 v[82:85], v[234:237], v[202:205], v[82:85]
	v_mfma_f32_16x16x32_bf16 v[78:81], v[226:229], v[210:213], v[78:81]
	v_mfma_f32_16x16x32_bf16 v[74:77], v[234:237], v[210:213], v[74:77]
	v_mfma_f32_16x16x32_bf16 v[70:73], v[226:229], v[218:221], v[70:73]
	v_mfma_f32_16x16x32_bf16 v[66:69], v[234:237], v[218:221], v[66:69]
	s_mov_b32 m0, s57
	v_lshl_add_u64 v[166:167], v[242:243], 0, s[38:39]
	s_barrier
	ds_read_b128 v[174:177], v168 offset:49152
	ds_read_b128 v[194:197], v168 offset:50176
	ds_read_b128 v[198:201], v168 offset:51200
	ds_read_b128 v[202:205], v168 offset:52224
	ds_read_b128 v[206:209], v168 offset:53248
	ds_read_b128 v[210:213], v168 offset:54272
	ds_read_b128 v[214:217], v168 offset:55296
	ds_read_b128 v[218:221], v168 offset:56320
	global_load_lds_dwordx4 v[166:167], off
	v_lshl_add_u64 v[166:167], v[244:245], 0, s[38:39]
	s_mov_b32 m0, s52
	s_nop 0
	global_load_lds_dwordx4 v[166:167], off
	s_barrier
	s_waitcnt lgkmcnt(0)
	s_waitcnt lgkmcnt(0)
	v_mfma_f32_16x16x32_bf16 v[62:65], v[130:133], v[174:177], v[62:65]
	v_mfma_f32_16x16x32_bf16 v[58:61], v[162:165], v[174:177], v[58:61]
	v_mfma_f32_16x16x32_bf16 v[54:57], v[130:133], v[198:201], v[54:57]
	v_mfma_f32_16x16x32_bf16 v[50:53], v[162:165], v[198:201], v[50:53]
	v_mfma_f32_16x16x32_bf16 v[46:49], v[130:133], v[206:209], v[46:49]
	v_mfma_f32_16x16x32_bf16 v[42:45], v[162:165], v[206:209], v[42:45]
	v_mfma_f32_16x16x32_bf16 v[38:41], v[130:133], v[214:217], v[38:41]
	v_mfma_f32_16x16x32_bf16 v[34:37], v[162:165], v[214:217], v[34:37]
	v_mfma_f32_16x16x32_bf16 v[62:65], v[134:137], v[194:197], v[62:65]
	v_mfma_f32_16x16x32_bf16 v[58:61], v[170:173], v[194:197], v[58:61]
	v_mfma_f32_16x16x32_bf16 v[54:57], v[134:137], v[202:205], v[54:57]
	v_mfma_f32_16x16x32_bf16 v[50:53], v[170:173], v[202:205], v[50:53]
	v_mfma_f32_16x16x32_bf16 v[46:49], v[134:137], v[210:213], v[46:49]
	v_mfma_f32_16x16x32_bf16 v[42:45], v[170:173], v[210:213], v[42:45]
	v_mfma_f32_16x16x32_bf16 v[38:41], v[134:137], v[218:221], v[38:41]
	v_mfma_f32_16x16x32_bf16 v[34:37], v[170:173], v[218:221], v[34:37]
	s_barrier
	s_add_i32 s0, s1, s16
	v_lshl_add_u64 v[130:131], v[246:247], 0, s[38:39]
	s_mov_b32 m0, s0
	s_nop 0
	global_load_lds_dwordx4 v[130:131], off
	v_lshl_add_u64 v[130:131], v[248:249], 0, s[38:39]
	s_add_i32 m0, s0, 0x2000
	s_nop 0
	global_load_lds_dwordx4 v[130:131], off
	s_waitcnt vmcnt(6)
	s_barrier
	v_mfma_f32_16x16x32_bf16 v[30:33], v[222:225], v[174:177], v[30:33]
	v_mfma_f32_16x16x32_bf16 v[26:29], v[230:233], v[174:177], v[26:29]
	v_mfma_f32_16x16x32_bf16 v[22:25], v[222:225], v[198:201], v[22:25]
	v_mfma_f32_16x16x32_bf16 v[18:21], v[230:233], v[198:201], v[18:21]
	v_mfma_f32_16x16x32_bf16 v[14:17], v[222:225], v[206:209], v[14:17]
	v_mfma_f32_16x16x32_bf16 v[10:13], v[230:233], v[206:209], v[10:13]
	v_mfma_f32_16x16x32_bf16 v[6:9], v[222:225], v[214:217], v[6:9]
	v_mfma_f32_16x16x32_bf16 v[2:5], v[230:233], v[214:217], v[2:5]
	v_mfma_f32_16x16x32_bf16 v[30:33], v[226:229], v[194:197], v[30:33]
	v_mfma_f32_16x16x32_bf16 v[26:29], v[234:237], v[194:197], v[26:29]
	v_mfma_f32_16x16x32_bf16 v[22:25], v[226:229], v[202:205], v[22:25]
	v_mfma_f32_16x16x32_bf16 v[18:21], v[234:237], v[202:205], v[18:21]
	v_mfma_f32_16x16x32_bf16 v[14:17], v[226:229], v[210:213], v[14:17]
	v_mfma_f32_16x16x32_bf16 v[10:13], v[234:237], v[210:213], v[10:13]
	v_mfma_f32_16x16x32_bf16 v[6:9], v[226:229], v[218:221], v[6:9]
	v_mfma_f32_16x16x32_bf16 v[2:5], v[234:237], v[218:221], v[2:5]
	s_add_u32 s82, s82, 0x100
	s_addc_u32 s83, s83, 0
	s_cmp_ge_i32 s13, s80
	v_lshl_add_u64 v[140:141], v[140:141], 0, s[22:23]
	s_barrier
	s_cbranch_scc1 .LBB0_422

; #define STAGE(bufoff,gbase,voff) do{ _Pragma("unroll") for(int _i=0;_i<2;++_i) \
;     __builtin_amdgcn_global_load_lds((const unsigned*)((const char*)(gbase)+(voff)[_i]),(LAS unsigned*)(lds+(bufoff)+ldsw+_i*8192),16,0,0);}while(0)
; #define LDA(dst,b,h) do{ _Pragma("unroll") for(int m=0;m<4;++m) _Pragma("unroll") for(int k=0;k<2;++k) dst[m][k]=*(const LAS bf16x8*)(lds+SA(b,h)+aoff+m*2048+k*1024);}while(0)
; #define LDB(dst,b,h) do{ _Pragma("unroll") for(int n=0;n<2;++n) _Pragma("unroll") for(int k=0;k<2;++k) dst[n][k]=*(const LAS bf16x8*)(lds+SB(b,h)+boff+n*2048+k*1024);}while(0)
; #define MMA(ai,bj,At_,Bt_) do{__builtin_amdgcn_s_setprio(1); \
;     _Pragma("unroll") for(int m=0;m<4;++m) _Pragma("unroll") for(int n=0;n<2;++n) _Pragma("unroll") for(int k=0;k<2;++k) \
;       acc[ai][bj][m][n]=__builtin_amdgcn_mfma_f32_16x16x32_bf16(Bt_[n][k],At_[m][k],acc[ai][bj][m][n],0,0,0); \
;     __builtin_amdgcn_s_setprio(0);}while(0)
; #define WAIT_V(n) asm volatile("s_waitcnt vmcnt(" #n ")":::"memory")
; #define WAIT_L(n) asm volatile("s_waitcnt lgkmcnt(" #n ")":::"memory")
; #define BAR __builtin_amdgcn_s_barrier()
; DEVI void gemm_tile(const GJob& jb, int brow, int bcol, unsigned char* shm_) {
;     ...
;   { LDB(B0,0,0); LDA(At,0,0); STAGE(SA(1,1),cA+(size_t)(nt-1)*128+hA,voffA);
;     BAR; WAIT_L(0); MMA(0,0,At,B0); BAR;
;     LDB(B1,0,1); BAR; WAIT_L(0); MMA(0,1,At,B1); BAR;
;     LDA(At,0,1); WAIT_V(4); BAR; WAIT_L(0); MMA(1,0,At,B0); MMA(1,1,At,B1); BAR; }
.LBB0_422:
	s_add_u32 s0, s10, s6
	s_addc_u32 s1, s11, s7
	s_add_u32 s0, s0, s26
	v_add_u32_e32 v168, 16, v161
	s_addc_u32 s1, s1, s27
	v_add_u32_e32 v144, 0x10000, v168
	v_add_u32_e32 v178, 16, v160
	v_lshl_add_u64 v[156:157], s[0:1], 0, v[0:1]
	s_add_i32 m0, s69, 0xc000
	ds_read_b128 v[130:133], v144
	ds_read_b128 v[134:137], v144 offset:1024
	ds_read_b128 v[140:143], v144 offset:2048
	ds_read_b128 v[144:147], v144 offset:3072
	ds_read_b128 v[148:151], v178
	ds_read_b128 v[152:155], v178 offset:1024
	ds_read_b128 v[160:163], v178 offset:2048
	ds_read_b128 v[164:167], v178 offset:3072
	ds_read_b128 v[170:173], v178 offset:4096
	ds_read_b128 v[174:177], v178 offset:5120
	ds_read_b128 v[194:197], v178 offset:6144
	ds_read_b128 v[198:201], v178 offset:7168
	global_load_lds_dwordx4 v[156:157], off
	v_lshl_add_u64 v[138:139], s[0:1], 0, v[138:139]
	s_add_i32 m0, s69, 0xe000
	s_nop 0
	global_load_lds_dwordx4 v[138:139], off
	s_barrier
	s_waitcnt lgkmcnt(0)
	s_waitcnt lgkmcnt(0)
	v_mfma_f32_16x16x32_bf16 v[122:125], v[130:133], v[148:151], v[122:125]
	v_mfma_f32_16x16x32_bf16 v[118:121], v[130:133], v[160:163], v[118:121]
	v_mfma_f32_16x16x32_bf16 v[114:117], v[140:143], v[160:163], v[114:117]
	v_mfma_f32_16x16x32_bf16 v[102:105], v[130:133], v[194:197], v[102:105]
	v_mfma_f32_16x16x32_bf16 v[98:101], v[140:143], v[194:197], v[98:101]
	v_mfma_f32_16x16x32_bf16 v[122:125], v[134:137], v[152:155], v[122:125]
	v_mfma_f32_16x16x32_bf16 v[126:129], v[140:143], v[148:151], v[126:129]
	v_mfma_f32_16x16x32_bf16 v[118:121], v[134:137], v[164:167], v[118:121]
	v_mfma_f32_16x16x32_bf16 v[114:117], v[144:147], v[164:167], v[114:117]
	v_mfma_f32_16x16x32_bf16 v[110:113], v[130:133], v[170:173], v[110:113]
	v_mfma_f32_16x16x32_bf16 v[106:109], v[140:143], v[170:173], v[106:109]
	v_mfma_f32_16x16x32_bf16 v[102:105], v[134:137], v[198:201], v[102:105]
	v_mfma_f32_16x16x32_bf16 v[98:101], v[144:147], v[198:201], v[98:101]
	v_mfma_f32_16x16x32_bf16 v[202:205], v[144:147], v[152:155], v[126:129]
	v_mfma_f32_16x16x32_bf16 v[206:209], v[134:137], v[174:177], v[110:113]
	v_mfma_f32_16x16x32_bf16 v[210:213], v[144:147], v[174:177], v[106:109]
	v_add_u32_e32 v0, 0x14000, v168
	s_barrier
	ds_read_b128 v[106:109], v0
	ds_read_b128 v[110:113], v0 offset:1024
	ds_read_b128 v[126:129], v0 offset:2048
	ds_read_b128 v[214:217], v0 offset:3072
	s_barrier
	s_waitcnt lgkmcnt(0)
	s_waitcnt lgkmcnt(0)
	v_mfma_f32_16x16x32_bf16 v[86:89], v[106:109], v[160:163], v[86:89]
	v_mfma_f32_16x16x32_bf16 v[82:85], v[126:129], v[160:163], v[82:85]
	v_mfma_f32_16x16x32_bf16 v[70:73], v[106:109], v[194:197], v[70:73]
	v_mfma_f32_16x16x32_bf16 v[66:69], v[126:129], v[194:197], v[66:69]
	v_mfma_f32_16x16x32_bf16 v[94:97], v[106:109], v[148:151], v[94:97]
	v_mfma_f32_16x16x32_bf16 v[90:93], v[126:129], v[148:151], v[90:93]
	v_mfma_f32_16x16x32_bf16 v[86:89], v[110:113], v[164:167], v[86:89]
	v_mfma_f32_16x16x32_bf16 v[82:85], v[214:217], v[164:167], v[82:85]
	v_mfma_f32_16x16x32_bf16 v[78:81], v[106:109], v[170:173], v[78:81]
	v_mfma_f32_16x16x32_bf16 v[74:77], v[126:129], v[170:173], v[74:77]
	v_mfma_f32_16x16x32_bf16 v[70:73], v[110:113], v[198:201], v[70:73]
	v_mfma_f32_16x16x32_bf16 v[66:69], v[214:217], v[198:201], v[66:69]
	v_mfma_f32_16x16x32_bf16 v[218:221], v[110:113], v[152:155], v[94:97]
	v_mfma_f32_16x16x32_bf16 v[148:151], v[214:217], v[152:155], v[90:93]
	v_mfma_f32_16x16x32_bf16 v[152:155], v[110:113], v[174:177], v[78:81]
	v_mfma_f32_16x16x32_bf16 v[160:163], v[214:217], v[174:177], v[74:77]
	s_barrier
	s_nop 0
	ds_read_b128 v[74:77], v178 offset:16384
	ds_read_b128 v[78:81], v178 offset:17408
	ds_read_b128 v[90:93], v178 offset:18432
	ds_read_b128 v[94:97], v178 offset:19456
	ds_read_b128 v[164:167], v178 offset:20480
	ds_read_b128 v[170:173], v178 offset:21504
	ds_read_b128 v[174:177], v178 offset:22528
	ds_read_b128 v[194:197], v178 offset:23552
	s_waitcnt vmcnt(4)
	s_barrier
	s_waitcnt lgkmcnt(0)
	s_waitcnt lgkmcnt(0)
	v_mfma_f32_16x16x32_bf16 v[62:65], v[130:133], v[74:77], v[62:65]
	v_mfma_f32_16x16x32_bf16 v[58:61], v[140:143], v[74:77], v[58:61]
	v_mfma_f32_16x16x32_bf16 v[54:57], v[130:133], v[90:93], v[54:57]
	v_mfma_f32_16x16x32_bf16 v[50:53], v[140:143], v[90:93], v[50:53]
	v_mfma_f32_16x16x32_bf16 v[38:41], v[130:133], v[174:177], v[38:41]
	v_mfma_f32_16x16x32_bf16 v[34:37], v[140:143], v[174:177], v[34:37]
	v_mfma_f32_16x16x32_bf16 v[62:65], v[134:137], v[78:81], v[62:65]
	v_mfma_f32_16x16x32_bf16 v[58:61], v[144:147], v[78:81], v[58:61]
	v_mfma_f32_16x16x32_bf16 v[54:57], v[134:137], v[94:97], v[54:57]
	v_mfma_f32_16x16x32_bf16 v[50:53], v[144:147], v[94:97], v[50:53]
	v_mfma_f32_16x16x32_bf16 v[46:49], v[130:133], v[164:167], v[46:49]
	v_mfma_f32_16x16x32_bf16 v[42:45], v[140:143], v[164:167], v[42:45]
	v_mfma_f32_16x16x32_bf16 v[38:41], v[134:137], v[194:197], v[38:41]
	v_mfma_f32_16x16x32_bf16 v[34:37], v[144:147], v[194:197], v[34:37]
	v_mfma_f32_16x16x32_bf16 v[198:201], v[134:137], v[170:173], v[46:49]
	v_mfma_f32_16x16x32_bf16 v[222:225], v[144:147], v[170:173], v[42:45]
	v_mfma_f32_16x16x32_bf16 v[22:25], v[106:109], v[90:93], v[22:25]
	v_mfma_f32_16x16x32_bf16 v[18:21], v[126:129], v[90:93], v[18:21]
	v_mfma_f32_16x16x32_bf16 v[6:9], v[106:109], v[174:177], v[6:9]
	v_mfma_f32_16x16x32_bf16 v[2:5], v[126:129], v[174:177], v[2:5]
	v_mfma_f32_16x16x32_bf16 v[30:33], v[106:109], v[74:77], v[30:33]
	v_mfma_f32_16x16x32_bf16 v[26:29], v[126:129], v[74:77], v[26:29]
	v_mfma_f32_16x16x32_bf16 v[22:25], v[110:113], v[94:97], v[22:25]
	v_mfma_f32_16x16x32_bf16 v[18:21], v[214:217], v[94:97], v[18:21]
	v_mfma_f32_16x16x32_bf16 v[14:17], v[106:109], v[164:167], v[14:17]
	v_mfma_f32_16x16x32_bf16 v[10:13], v[126:129], v[164:167], v[10:13]
	v_mfma_f32_16x16x32_bf16 v[6:9], v[110:113], v[194:197], v[6:9]
	v_mfma_f32_16x16x32_bf16 v[2:5], v[214:217], v[194:197], v[2:5]
	v_mfma_f32_16x16x32_bf16 v[130:133], v[110:113], v[78:81], v[30:33]
	v_mfma_f32_16x16x32_bf16 v[134:137], v[214:217], v[78:81], v[26:29]
	v_mfma_f32_16x16x32_bf16 v[138:141], v[110:113], v[170:173], v[14:17]
	v_mfma_f32_16x16x32_bf16 v[142:145], v[214:217], v[170:173], v[10:13]
	v_add_u32_e32 v0, 0x18000, v168
	s_barrier
; #define LDA(dst,b,h) do{ _Pragma("unroll") for(int m=0;m<4;++m) _Pragma("unroll") for(int k=0;k<2;++k) dst[m][k]=*(const LAS bf16x8*)(lds+SA(b,h)+aoff+m*2048+k*1024);}while(0)
; #define LDB(dst,b,h) do{ _Pragma("unroll") for(int n=0;n<2;++n) _Pragma("unroll") for(int k=0;k<2;++k) dst[n][k]=*(const LAS bf16x8*)(lds+SB(b,h)+boff+n*2048+k*1024);}while(0)
; #define MMA(ai,bj,At_,Bt_) do{__builtin_amdgcn_s_setprio(1); \
;     _Pragma("unroll") for(int m=0;m<4;++m) _Pragma("unroll") for(int n=0;n<2;++n) _Pragma("unroll") for(int k=0;k<2;++k) \
;       acc[ai][bj][m][n]=__builtin_amdgcn_mfma_f32_16x16x32_bf16(Bt_[n][k],At_[m][k],acc[ai][bj][m][n],0,0,0); \
;     __builtin_amdgcn_s_setprio(0);}while(0)
; #define WAIT_V(n) asm volatile("s_waitcnt vmcnt(" #n ")":::"memory")
; #define WAIT_L(n) asm volatile("s_waitcnt lgkmcnt(" #n ")":::"memory")
; #define BAR __builtin_amdgcn_s_barrier()
; DEVI void gemm_tile(const GJob& jb, int brow, int bcol, unsigned char* shm_) {
;     ...
;   { LDB(B0,1,0); LDA(At,1,0); WAIT_V(2); BAR; WAIT_L(0); MMA(0,0,At,B0); BAR;
;     LDB(B1,1,1); WAIT_V(0); BAR; WAIT_L(0); MMA(0,1,At,B1); BAR;
;     LDA(At,1,1); BAR; WAIT_L(0); MMA(1,0,At,B0); MMA(1,1,At,B1); BAR; }
;   if (wr == 0) BAR;
	ds_read_b128 v[10:13], v0
	ds_read_b128 v[14:17], v0 offset:1024
	ds_read_b128 v[164:167], v0 offset:2048
	ds_read_b128 v[170:173], v0 offset:3072
	ds_read_b128 v[26:29], v178 offset:32768
	ds_read_b128 v[30:33], v178 offset:33792
	ds_read_b128 v[42:45], v178 offset:34816
	ds_read_b128 v[46:49], v178 offset:35840
	ds_read_b128 v[174:177], v178 offset:36864
	ds_read_b128 v[194:197], v178 offset:37888
	ds_read_b128 v[214:217], v178 offset:38912
	ds_read_b128 v[226:229], v178 offset:39936
	s_waitcnt vmcnt(2)
	s_barrier
	s_waitcnt lgkmcnt(0)
	s_waitcnt lgkmcnt(0)
	v_mfma_f32_16x16x32_bf16 v[74:77], v[10:13], v[26:29], v[122:125]
	v_mfma_f32_16x16x32_bf16 v[126:129], v[14:17], v[30:33], v[74:77]
	v_mfma_f32_16x16x32_bf16 v[74:77], v[164:167], v[26:29], v[202:205]
	v_mfma_f32_16x16x32_bf16 v[122:125], v[170:173], v[30:33], v[74:77]
	v_mfma_f32_16x16x32_bf16 v[74:77], v[10:13], v[42:45], v[118:121]
	v_mfma_f32_16x16x32_bf16 v[110:113], v[14:17], v[46:49], v[74:77]
	v_mfma_f32_16x16x32_bf16 v[74:77], v[164:167], v[42:45], v[114:117]
	v_mfma_f32_16x16x32_bf16 v[106:109], v[170:173], v[46:49], v[74:77]
	v_mfma_f32_16x16x32_bf16 v[74:77], v[10:13], v[174:177], v[206:209]
	v_mfma_f32_16x16x32_bf16 v[94:97], v[14:17], v[194:197], v[74:77]
	v_mfma_f32_16x16x32_bf16 v[74:77], v[164:167], v[174:177], v[210:213]
	v_mfma_f32_16x16x32_bf16 v[90:93], v[170:173], v[194:197], v[74:77]
	v_mfma_f32_16x16x32_bf16 v[74:77], v[10:13], v[214:217], v[102:105]
	v_mfma_f32_16x16x32_bf16 v[78:81], v[14:17], v[226:229], v[74:77]
	v_mfma_f32_16x16x32_bf16 v[74:77], v[164:167], v[214:217], v[98:101]
	v_mfma_f32_16x16x32_bf16 v[74:77], v[170:173], v[226:229], v[74:77]
	v_add_u32_e32 v0, 0x1c000, v168
	s_barrier
	ds_read_b128 v[202:205], v0
	ds_read_b128 v[206:209], v0 offset:1024
	ds_read_b128 v[210:213], v0 offset:2048
	ds_read_b128 v[230:233], v0 offset:3072
	s_waitcnt vmcnt(0)
	s_barrier
	s_waitcnt lgkmcnt(0)
	s_waitcnt lgkmcnt(0)
	v_mfma_f32_16x16x32_bf16 v[98:101], v[202:205], v[26:29], v[218:221]
	v_mfma_f32_16x16x32_bf16 v[26:29], v[210:213], v[26:29], v[148:151]
	v_mfma_f32_16x16x32_bf16 v[114:117], v[230:233], v[30:33], v[26:29]
	v_mfma_f32_16x16x32_bf16 v[26:29], v[202:205], v[42:45], v[86:89]
	v_mfma_f32_16x16x32_bf16 v[102:105], v[206:209], v[46:49], v[26:29]
	v_mfma_f32_16x16x32_bf16 v[26:29], v[210:213], v[42:45], v[82:85]
	v_mfma_f32_16x16x32_bf16 v[118:121], v[206:209], v[30:33], v[98:101]
	v_mfma_f32_16x16x32_bf16 v[98:101], v[230:233], v[46:49], v[26:29]
	v_mfma_f32_16x16x32_bf16 v[26:29], v[202:205], v[174:177], v[152:155]
	v_mfma_f32_16x16x32_bf16 v[86:89], v[206:209], v[194:197], v[26:29]
	v_mfma_f32_16x16x32_bf16 v[26:29], v[210:213], v[174:177], v[160:163]
	v_mfma_f32_16x16x32_bf16 v[82:85], v[230:233], v[194:197], v[26:29]
	v_mfma_f32_16x16x32_bf16 v[26:29], v[202:205], v[214:217], v[70:73]
	v_mfma_f32_16x16x32_bf16 v[70:73], v[206:209], v[226:229], v[26:29]
	v_mfma_f32_16x16x32_bf16 v[26:29], v[210:213], v[214:217], v[66:69]
	v_mfma_f32_16x16x32_bf16 v[66:69], v[230:233], v[226:229], v[26:29]
	s_barrier
	ds_read_b128 v[146:149], v178 offset:49152
	ds_read_b128 v[150:153], v178 offset:50176
	ds_read_b128 v[154:157], v178 offset:51200
	ds_read_b128 v[160:163], v178 offset:52224
	ds_read_b128 v[174:177], v178 offset:53248
	ds_read_b128 v[194:197], v178 offset:54272
	ds_read_b128 v[214:217], v178 offset:55296
	ds_read_b128 v[218:221], v178 offset:56320
	s_barrier
	s_waitcnt lgkmcnt(0)
	s_waitcnt lgkmcnt(0)
	v_mfma_f32_16x16x32_bf16 v[26:29], v[10:13], v[146:149], v[62:65]
	v_mfma_f32_16x16x32_bf16 v[62:65], v[14:17], v[150:153], v[26:29]
	v_mfma_f32_16x16x32_bf16 v[26:29], v[164:167], v[146:149], v[58:61]
	v_mfma_f32_16x16x32_bf16 v[58:61], v[170:173], v[150:153], v[26:29]
	v_mfma_f32_16x16x32_bf16 v[26:29], v[10:13], v[154:157], v[54:57]
	v_mfma_f32_16x16x32_bf16 v[46:49], v[14:17], v[160:163], v[26:29]
	v_mfma_f32_16x16x32_bf16 v[26:29], v[164:167], v[154:157], v[50:53]
	v_mfma_f32_16x16x32_bf16 v[42:45], v[170:173], v[160:163], v[26:29]
	v_mfma_f32_16x16x32_bf16 v[26:29], v[10:13], v[174:177], v[198:201]
	v_mfma_f32_16x16x32_bf16 v[10:13], v[10:13], v[214:217], v[38:41]
	v_mfma_f32_16x16x32_bf16 v[30:33], v[14:17], v[194:197], v[26:29]
	v_mfma_f32_16x16x32_bf16 v[26:29], v[164:167], v[174:177], v[222:225]
	v_mfma_f32_16x16x32_bf16 v[14:17], v[14:17], v[218:221], v[10:13]
	v_mfma_f32_16x16x32_bf16 v[10:13], v[164:167], v[214:217], v[34:37]
	v_mfma_f32_16x16x32_bf16 v[26:29], v[170:173], v[194:197], v[26:29]
	v_mfma_f32_16x16x32_bf16 v[10:13], v[170:173], v[218:221], v[10:13]
	v_mfma_f32_16x16x32_bf16 v[34:37], v[202:205], v[146:149], v[130:133]
	v_mfma_f32_16x16x32_bf16 v[54:57], v[206:209], v[150:153], v[34:37]
	v_mfma_f32_16x16x32_bf16 v[34:37], v[210:213], v[146:149], v[134:137]
	v_mfma_f32_16x16x32_bf16 v[18:21], v[210:213], v[154:157], v[18:21]
	v_mfma_f32_16x16x32_bf16 v[50:53], v[230:233], v[150:153], v[34:37]
	v_mfma_f32_16x16x32_bf16 v[22:25], v[202:205], v[154:157], v[22:25]
	v_mfma_f32_16x16x32_bf16 v[34:37], v[230:233], v[160:163], v[18:21]
	v_mfma_f32_16x16x32_bf16 v[18:21], v[202:205], v[174:177], v[138:141]
	v_mfma_f32_16x16x32_bf16 v[38:41], v[206:209], v[160:163], v[22:25]
	v_mfma_f32_16x16x32_bf16 v[22:25], v[206:209], v[194:197], v[18:21]
	v_mfma_f32_16x16x32_bf16 v[18:21], v[210:213], v[174:177], v[142:145]
	v_mfma_f32_16x16x32_bf16 v[6:9], v[202:205], v[214:217], v[6:9]
	v_mfma_f32_16x16x32_bf16 v[2:5], v[210:213], v[214:217], v[2:5]
	v_mfma_f32_16x16x32_bf16 v[18:21], v[230:233], v[194:197], v[18:21]
	v_mfma_f32_16x16x32_bf16 v[6:9], v[206:209], v[218:221], v[6:9]
	v_mfma_f32_16x16x32_bf16 v[2:5], v[230:233], v[218:221], v[2:5]
	s_cmpk_lt_u32 s46, 0x100
	s_barrier
	s_cbranch_scc0 .LBB0_424
	s_barrier
; DEVI float bf_lo(unsigned u) { return __uint_as_float(u << 16); }
; DEVI float bf_hi(unsigned u) { return __uint_as_float(u & 0xffff0000u); }
; DEVI float sigmoidf_(float x) { return 1.f / (1.f + __expf(-x)); }
; DEVI u32x4 pack8(f32x4 a, f32x4 b) { u32x4 o; o.x = cvt_pk_bf16(a[0], a[1]); o.y = cvt_pk_bf16(a[2], a[3]); o.z = cvt_pk_bf16(b[0], b[1]); o.w = cvt_pk_bf16(b[2], b[3]); return o; }
; DEVI void gemm_epi(const GJob& jb, int row, int col, f32x4 v0, f32x4 v1) {
;   const int mode = jb.mode;
;   if (mode == 0) { *(u32x4*)((bf16_t*)jb.out + (size_t)row * jb.ldo + col) = pack8(v0, v1); }
;   else if (mode == 1) { float* p = (float*)jb.out + (size_t)row * jb.ldo + col; *(f32x4*)p = v0; *(f32x4*)(p + 4) = v1; }
;   else if (mode == 2) { f32x4 s0, s1; for (int i = 0; i < 4; ++i) { s0[i] = sigmoidf_(v0[i]); s1[i] = sigmoidf_(v1[i]); } *(u32x4*)((bf16_t*)jb.out + (size_t)row * jb.ldo + col) = pack8(s0, s1); }
;   else if (mode == 7) {
;     const u32x4 g = *(const u32x4*)((const bf16_t*)jb.aux + (size_t)row * NGATE + 2 * 2048 + col);
;     const f32x4 g0 = {bf_lo(g.x), bf_hi(g.x), bf_lo(g.y), bf_hi(g.y)}, g1 = {bf_lo(g.z), bf_hi(g.z), bf_lo(g.w), bf_hi(g.w)};
;     *(u32x4*)((bf16_t*)jb.out + (size_t)row * 2048 + col) = pack8(g0 * v0, g1 * v1);
.LBB0_424:
	s_setprio 0
	v_or_b32_e32 v0, s43, v159
	v_add_u32_e32 v132, s47, v0
	v_or_b32_e32 v0, s12, v158
	v_ashrrev_i32_e32 v133, 31, v132
	v_or_b32_e32 v130, s68, v0
	s_cmp_eq_u32 s71, 6
	s_cbranch_scc1 .Lepi6
	v_mad_i64_i32 v[136:137], s[0:1], v132, s33, 0
	v_lshlrev_b64 v[134:135], 12, v[132:133]
	s_mov_b64 s[12:13], -1
	s_mov_b64 s[10:11], 0
	s_cmp_lt_i32 s71, 2
	s_mov_b64 s[8:9], 0
	s_cbranch_scc1 .LBB0_433
	s_cmp_gt_i32 s71, 6
	s_cbranch_scc0 .LBB0_429
	s_cmp_eq_u32 s71, 7
	s_mov_b64 s[8:9], -1
	s_cbranch_scc0 .LBB0_428
	v_ashrrev_i32_e32 v131, 31, v130
	v_lshl_add_u64 v[138:139], s[94:95], 0, v[136:137]
	v_lshlrev_b64 v[142:143], 1, v[130:131]
	v_lshl_add_u64 v[138:139], v[138:139], 0, v[142:143]
	v_add_co_u32_e32 v138, vcc, 0x2000, v138
	v_lshl_add_u64 v[144:145], s[90:91], 0, v[134:135]
	s_nop 0
	v_addc_co_u32_e32 v139, vcc, 0, v139, vcc
	flat_load_dwordx4 v[138:141], v[138:139]
	v_lshl_add_u64 v[142:143], v[144:145], 0, v[142:143]
	s_mov_b64 s[8:9], 0
	s_waitcnt vmcnt(0) lgkmcnt(0)
	v_lshlrev_b32_e32 v144, 16, v138
	v_and_b32_e32 v145, 0xffff0000, v138
	v_lshlrev_b32_e32 v138, 16, v139
	v_and_b32_e32 v139, 0xffff0000, v139
	v_lshlrev_b32_e32 v146, 16, v140
	v_and_b32_e32 v147, 0xffff0000, v140
	v_lshlrev_b32_e32 v140, 16, v141
	v_and_b32_e32 v141, 0xffff0000, v141
	v_pk_mul_f32 v[148:149], v[128:129], v[138:139]
	v_pk_mul_f32 v[138:139], v[126:127], v[144:145]
	v_pk_mul_f32 v[144:145], v[124:125], v[140:141]
	v_pk_mul_f32 v[140:141], v[122:123], v[146:147]
	v_cvt_pk_bf16_f32 v138, v138, v139
	v_cvt_pk_bf16_f32 v139, v148, v149
	s_nop 0
	v_cvt_pk_bf16_f32 v140, v140, v141
	v_cvt_pk_bf16_f32 v141, v144, v145
	flat_store_dwordx4 v[142:143], v[138:141]
